# MLA attention loop trimmed and PV reads pipelined; GEMM loop m0 writes reordered to drop six s_nop per iteration; max canonicalisation folded
# speedup vs baseline: 1.0239x; 1.0052x over previous
; DI float shx(float v, int mask, int lane) { return __builtin_bit_cast(float, __builtin_amdgcn_ds_bpermute((lane ^ mask) << 2, __builtin_bit_cast(int, v))); }
; DI float ex2(float x) { return __builtin_amdgcn_exp2f(x); }
; template <int MODE>
; DI void attn_unit(LAS unsigned char* lds, const bf16_t* Qg, int ldq, const bf16_t* Kg, int ldk, const bf16_t* VTg, int ldvt, bf16_t* Og, int ldo,
;                   int q0, int NT, const float* gout, const float* relb, float lam, float osc, const float* qgain) {
;     ...
;                 float mx = __builtin_fmaxf(__builtin_fmaxf(p0[0], p0[1]), p0[2]);
; #pragma unroll
;                 for (int i = 3; i < 15; i += 2) mx = __builtin_fmaxf(__builtin_fmaxf(mx, p0[i]), p0[i + 1]);
;                 mx = __builtin_fmaxf(mx, p0[15]);
; #pragma unroll
;                 for (int i = 0; i < 16; i += 2) mx = __builtin_fmaxf(__builtin_fmaxf(mx, p1[i]), p1[i + 1]);
;                 mx = __builtin_fmaxf(mx, shx(mx, 32, lane));
;                 if (t == 0 || __any(mx > 8.f)) {
;                     const float dl = (t == 0) ? mx : __builtin_fmaxf(mx, 0.f);
;                     mhat += dl;
; #pragma unroll
;                     for (int i = 0; i < 16; ++i) { p0[i] -= dl; p1[i] -= dl; }
; #pragma unroll
;                     for (int i = 0; i < 16; ++i) negm[i] = c15 - mhat;
;                     if (t > 0) { const float f = ex2(-dl); lrun *= f;
; #pragma unroll
;                         for (int d = 0; d < NDB; ++d)
; #pragma unroll
;                             for (int i = 0; i < 16; ++i) o[d][i] *= f; }
;                 }
.LBB0_193:
	s_nop 7
	v_max_f32_e32 v0, v84, v85
	v_max3_f32 v0, v0, v86, v87
	v_max3_f32 v0, v0, v88, v89
	v_max3_f32 v0, v0, v90, v91
	v_max3_f32 v0, v0, v92, v93
	v_max3_f32 v0, v0, v94, v95
	v_max3_f32 v0, v0, v96, v97
	v_max3_f32 v0, v0, v98, v99
	v_max3_f32 v0, v0, v100, v101
	v_max3_f32 v0, v0, v102, v103
	v_max3_f32 v0, v0, v104, v105
	v_max3_f32 v0, v0, v106, v107
	v_max3_f32 v0, v0, v108, v109
	v_max3_f32 v0, v0, v110, v111
	v_max3_f32 v0, v0, v112, v113
	v_max3_f32 v0, v0, v114, v115
	ds_bpermute_b32 v162, v151, v0
	s_mov_b32 s2, 0x41000000
	s_waitcnt lgkmcnt(0)
	v_max_f32_e32 v162, v162, v162
	v_max_f32_e32 v0, v0, v162
	v_cmp_lt_f32_e32 vcc, s2, v0
	s_cbranch_vccz .LBB0_195
	v_max_f32_e32 v0, v0, v0
	v_max_f32_e32 v0, 0, v0
	v_exp_f32_e64 v70, -v0
	v_add_f32_e32 v152, v152, v0
	v_sub_f32_e32 v68, v66, v152
	v_pk_add_f32 v[100:101], v[100:101], v[0:1] op_sel_hi:[1,0] neg_lo:[0,1] neg_hi:[0,1]
	v_pk_add_f32 v[102:103], v[102:103], v[0:1] op_sel_hi:[1,0] neg_lo:[0,1] neg_hi:[0,1]
	v_pk_add_f32 v[104:105], v[104:105], v[0:1] op_sel_hi:[1,0] neg_lo:[0,1] neg_hi:[0,1]
	v_pk_add_f32 v[106:107], v[106:107], v[0:1] op_sel_hi:[1,0] neg_lo:[0,1] neg_hi:[0,1]
	v_pk_add_f32 v[108:109], v[108:109], v[0:1] op_sel_hi:[1,0] neg_lo:[0,1] neg_hi:[0,1]
	v_pk_add_f32 v[110:111], v[110:111], v[0:1] op_sel_hi:[1,0] neg_lo:[0,1] neg_hi:[0,1]
	v_pk_add_f32 v[112:113], v[112:113], v[0:1] op_sel_hi:[1,0] neg_lo:[0,1] neg_hi:[0,1]
	v_pk_add_f32 v[114:115], v[114:115], v[0:1] op_sel_hi:[1,0] neg_lo:[0,1] neg_hi:[0,1]
	v_pk_add_f32 v[84:85], v[84:85], v[0:1] op_sel_hi:[1,0] neg_lo:[0,1] neg_hi:[0,1]
	v_pk_add_f32 v[86:87], v[86:87], v[0:1] op_sel_hi:[1,0] neg_lo:[0,1] neg_hi:[0,1]
	v_pk_add_f32 v[88:89], v[88:89], v[0:1] op_sel_hi:[1,0] neg_lo:[0,1] neg_hi:[0,1]
	v_pk_add_f32 v[90:91], v[90:91], v[0:1] op_sel_hi:[1,0] neg_lo:[0,1] neg_hi:[0,1]
	v_pk_add_f32 v[92:93], v[92:93], v[0:1] op_sel_hi:[1,0] neg_lo:[0,1] neg_hi:[0,1]
	v_pk_add_f32 v[94:95], v[94:95], v[0:1] op_sel_hi:[1,0] neg_lo:[0,1] neg_hi:[0,1]
	v_pk_add_f32 v[96:97], v[96:97], v[0:1] op_sel_hi:[1,0] neg_lo:[0,1] neg_hi:[0,1]
	v_pk_add_f32 v[98:99], v[98:99], v[0:1] op_sel_hi:[1,0] neg_lo:[0,1] neg_hi:[0,1]
	v_pk_mul_f32 v[64:65], v[64:65], v[70:71] op_sel_hi:[1,0]
	v_pk_mul_f32 v[62:63], v[62:63], v[70:71] op_sel_hi:[1,0]
	v_pk_mul_f32 v[60:61], v[60:61], v[70:71] op_sel_hi:[1,0]
	v_pk_mul_f32 v[58:59], v[58:59], v[70:71] op_sel_hi:[1,0]
	v_pk_mul_f32 v[56:57], v[56:57], v[70:71] op_sel_hi:[1,0]
	v_pk_mul_f32 v[54:55], v[54:55], v[70:71] op_sel_hi:[1,0]
	v_pk_mul_f32 v[52:53], v[52:53], v[70:71] op_sel_hi:[1,0]
	v_pk_mul_f32 v[50:51], v[50:51], v[70:71] op_sel_hi:[1,0]
	v_pk_mul_f32 v[48:49], v[48:49], v[70:71] op_sel_hi:[1,0]
	v_pk_mul_f32 v[46:47], v[46:47], v[70:71] op_sel_hi:[1,0]
	v_pk_mul_f32 v[44:45], v[44:45], v[70:71] op_sel_hi:[1,0]
	v_pk_mul_f32 v[42:43], v[42:43], v[70:71] op_sel_hi:[1,0]
	v_pk_mul_f32 v[40:41], v[40:41], v[70:71] op_sel_hi:[1,0]
	v_pk_mul_f32 v[38:39], v[38:39], v[70:71] op_sel_hi:[1,0]
	v_pk_mul_f32 v[36:37], v[36:37], v[70:71] op_sel_hi:[1,0]
	v_pk_mul_f32 v[34:35], v[34:35], v[70:71] op_sel_hi:[1,0]
	v_pk_mul_f32 v[32:33], v[32:33], v[70:71] op_sel_hi:[1,0]
	v_pk_mul_f32 v[30:31], v[30:31], v[70:71] op_sel_hi:[1,0]
	v_pk_mul_f32 v[28:29], v[28:29], v[70:71] op_sel_hi:[1,0]
	v_pk_mul_f32 v[26:27], v[26:27], v[70:71] op_sel_hi:[1,0]
	v_pk_mul_f32 v[24:25], v[24:25], v[70:71] op_sel_hi:[1,0]
	v_pk_mul_f32 v[22:23], v[22:23], v[70:71] op_sel_hi:[1,0]
	v_pk_mul_f32 v[20:21], v[20:21], v[70:71] op_sel_hi:[1,0]
	v_pk_mul_f32 v[18:19], v[18:19], v[70:71] op_sel_hi:[1,0]
	v_pk_mul_f32 v[16:17], v[16:17], v[70:71] op_sel_hi:[1,0]
	v_pk_mul_f32 v[14:15], v[14:15], v[70:71] op_sel_hi:[1,0]
	v_pk_mul_f32 v[12:13], v[12:13], v[70:71] op_sel_hi:[1,0]
	v_pk_mul_f32 v[10:11], v[10:11], v[70:71] op_sel_hi:[1,0]
	v_pk_mul_f32 v[8:9], v[8:9], v[70:71] op_sel_hi:[1,0]
	v_pk_mul_f32 v[6:7], v[6:7], v[70:71] op_sel_hi:[1,0]
	v_pk_mul_f32 v[4:5], v[4:5], v[70:71] op_sel_hi:[1,0]
	v_pk_mul_f32 v[2:3], v[2:3], v[70:71] op_sel_hi:[1,0]
	v_mul_f32_e32 v153, v153, v70
	v_mov_b32_e32 v69, v68
	v_mov_b32_e32 v70, v68
	v_mov_b32_e32 v71, v68
	v_mov_b32_e32 v72, v68
	v_mov_b32_e32 v73, v68
	v_mov_b32_e32 v74, v68
	v_mov_b32_e32 v75, v68
	v_mov_b32_e32 v76, v68
	v_mov_b32_e32 v77, v68
	v_mov_b32_e32 v78, v68
	v_mov_b32_e32 v79, v68
	v_mov_b32_e32 v80, v68
	v_mov_b32_e32 v81, v68
	v_mov_b32_e32 v82, v68
	v_mov_b32_e32 v83, v68

; template <int MODE>
; DI void attn_unit(LAS unsigned char* lds, const bf16_t* Qg, int ldq, const bf16_t* Kg, int ldk, const bf16_t* VTg, int ldvt, bf16_t* Og, int ldo,
;                   int q0, int NT, const float* gout, const float* relb, float lam, float osc, const float* qgain) {
;     ...
;     auto pvdo = [&](const int vbi, const u32x4 (&pp)[4]) {
;         const LAS unsigned char* Vb = lds + VB0 + vbi * VBSZ + (r32 + (MODE == 2 ? mm * 64 : 0)) * VSTR + hi * 8;
; #pragma unroll
;         for (int d = 0; d < NDB; ++d)
; #pragma unroll
;             for (int ks = 0; ks < 4; ++ks) { const int kb = 32 * (ks >> 1) + 16 * (ks & 1);
;                 const s16x4 lo = *(const LAS s16x4*)(Vb + d * 32 * VSTR + kb * 2), hh = *(const LAS s16x4*)(Vb + d * 32 * VSTR + kb * 2 + 16);
;                 const bf16x8 vf = __builtin_shufflevector(lo, hh, 0, 1, 2, 3, 4, 5, 6, 7);
;                 o[d] = MFMA32(vf, __builtin_bit_cast(bf16x8, pp[ks]), o[d]); }
;     };
;     int vcur = 0;
;     for (int t = 0; t < NT; ++t) {
;         const int cur = t & 1;
;         const int vnext = vcur == 2 ? 0 : vcur + 1, vprev = vcur == 0 ? 2 : vcur - 1;
;         if (MODE == 2 && SB_EARLY && t > 0) {
;             const LAS unsigned* fl = (const LAS unsigned*)(lds + FLG) + ((t - 1) & 1) * 8; unsigned any = 0;
; #pragma unroll
;             for (int w = 0; w < 8; ++w) any |= fl[w];
;             if (any == 0u) break;
;         }
;         if (t + 1 < NT) AT_GLOAD(AT_KEY0(t + 1));
;         const int key0 = AT_KEY0(t);
;         bool active;
;         if (MODE == 2) active = (NT - 1 - t) <= TD; else active = t < ntw;
;         bool alive = true;
;         if (MODE == 2) alive = !active || __any(R > -150.f);
;         if (skew && t >= 1 && (t - 1) < ntw) pvdo(vprev, pk);
;         if (active && alive) {
;             const LAS unsigned char* Kb = lds + (cur ? KB1 : KB0) + r32 * KSTR + mm * 128 + hi * 16;
;             f32x16 p0, p1;
; #pragma unroll
;             for (int s = 0; s < NS; ++s) { const bf16x8 a0 = *(const LAS bf16x8*)(Kb + s * 32), a1 = *(const LAS bf16x8*)(Kb + 32 * KSTR + s * 32);
;                 if (s == 0) { p0 = MFMA32(a0, qf[0], negm); p1 = MFMA32(a1, qf[0], negm); } else { p0 = MFMA32(a0, qf[s], p0); p1 = MFMA32(a1, qf[s], p1); } }
;             if (MODE != 2) {
;                 if (MODE == 0) {
;                     const int qmin = q0 + 32 * rg;
.LBB0_233:
	s_or_b64 exec, exec, s[6:7]
	s_add_i32 s2, s11, 1
	s_cmp_lg_u32 s11, 2
	s_cselect_b32 s11, s2, 0
	s_mul_i32 s14, s11, 0x4400
	v_add_u32_e32 v0, s14, v162
	s_add_i32 s13, s13, 1
	s_mov_b64 s[2:3], 0xc000
	v_add_u32_e32 v0, 0x8800, v0
	v_lshl_add_u64 v[138:139], v[138:139], 0, s[2:3]
	v_lshl_add_u64 v[140:141], v[140:141], 0, s[2:3]
	s_cmp_eq_u32 s9, s13
	v_lshl_add_u64 v[142:143], v[142:143], 0, s[34:35]
	ds_write2_b64 v0, v[2:3], v[4:5] offset1:1
	s_waitcnt lgkmcnt(0)
	s_barrier
	s_cbranch_scc1 .LBB0_250
.LBB0_234:
	global_load_dwordx4 v[96:99], v[138:139], off
.LBB0_236:
	s_and_saveexec_b64 s[6:7], s[40:41]
	s_cbranch_execz .LBB0_238
	global_load_dwordx4 v[100:103], v[140:141], off
.LBB0_238:
	s_or_b64 exec, exec, s[6:7]
	global_load_dwordx4 v[2:5], v[142:143], off
	s_add_i32 s2, s13, 3
	s_cmp_le_i32 s2, s10
	s_cselect_b64 s[6:7], -1, 0
	s_and_b64 s[6:7], s[0:1], s[6:7]
	s_andn2_b64 vcc, exec, s[6:7]
	s_cbranch_vccnz .LBB0_240
	s_mul_i32 s3, s11, 0x4400
	s_addk_i32 s3, 0xbc00
	s_cmp_lg_u32 s11, 0
	s_cselect_b32 s3, s3, 0x8800
	v_add_u32_e32 v0, s3, v163
	v_add_u32_e32 v236, 0x8800, v0
	v_add_u32_e32 v237, 0x9800, v0
	ds_read2_b64 v[212:215], v236 offset1:2
	ds_read2_b64 v[216:219], v236 offset0:4 offset1:6
	ds_read2_b64 v[220:223], v236 offset0:8 offset1:10
	ds_read2_b64 v[224:227], v236 offset0:12 offset1:14
	s_waitcnt lgkmcnt(2)
	v_mfma_f32_32x32x16_bf16 v[32:47], v[212:215], v[68:71], v[32:47]
	v_mfma_f32_32x32x16_bf16 v[32:47], v[216:219], v[64:67], v[32:47]
	ds_read2_b64 v[212:215], v237 offset0:32 offset1:34
	ds_read2_b64 v[216:219], v237 offset0:36 offset1:38
	s_waitcnt lgkmcnt(2)
	v_mfma_f32_32x32x16_bf16 v[32:47], v[220:223], v[10:13], v[32:47]
	v_mfma_f32_32x32x16_bf16 v[32:47], v[224:227], v[6:9], v[32:47]
	ds_read2_b64 v[220:223], v237 offset0:40 offset1:42
	ds_read2_b64 v[224:227], v237 offset0:44 offset1:46
	s_waitcnt lgkmcnt(2)
	v_mfma_f32_32x32x16_bf16 v[16:31], v[212:215], v[68:71], v[16:31]
	v_mfma_f32_32x32x16_bf16 v[16:31], v[216:219], v[64:67], v[16:31]
	s_waitcnt lgkmcnt(0)
	v_mfma_f32_32x32x16_bf16 v[16:31], v[220:223], v[10:13], v[16:31]
	v_mfma_f32_32x32x16_bf16 v[16:31], v[224:227], v[6:9], v[16:31]
.LBB0_240:
	s_and_b32 s6, s2, 1
	s_cmp_gt_i32 s2, s12
	s_cbranch_scc1 .LBB0_246
	s_cmp_eq_u32 s6, 0
	s_cselect_b32 s2, 0, 0x4400
	v_add_u32_e32 v0, s2, v164
	ds_read_b128 v[6:9], v0 offset:6656
	ds_read_b128 v[10:13], v0
	ds_read_b128 v[144:147], v0 offset:32
	s_mov_b32 s2, 0x41000000
	s_waitcnt lgkmcnt(0)
	v_mfma_f32_32x32x16_bf16 v[64:79], v[6:9], v[124:127], v[48:63]
	ds_read_b128 v[6:9], v0 offset:6688
	v_mfma_f32_32x32x16_bf16 v[80:95], v[10:13], v[124:127], v[48:63]
	v_mfma_f32_32x32x16_bf16 v[80:95], v[144:147], v[116:119], v[80:95]
	s_waitcnt lgkmcnt(0)
	v_mfma_f32_32x32x16_bf16 v[64:79], v[6:9], v[116:119], v[64:79]
	ds_read_b128 v[6:9], v0 offset:6720
	ds_read_b128 v[10:13], v0 offset:64
	s_waitcnt lgkmcnt(0)
	v_mfma_f32_32x32x16_bf16 v[80:95], v[10:13], v[120:123], v[80:95]
	v_mfma_f32_32x32x16_bf16 v[64:79], v[6:9], v[120:123], v[64:79]
	ds_read_b128 v[6:9], v0 offset:6752
	ds_read_b128 v[10:13], v0 offset:96
	s_waitcnt lgkmcnt(0)
	v_mfma_f32_32x32x16_bf16 v[80:95], v[10:13], v[112:115], v[80:95]
	v_mfma_f32_32x32x16_bf16 v[64:79], v[6:9], v[112:115], v[64:79]
	ds_read_b128 v[6:9], v0 offset:6784
	ds_read_b128 v[10:13], v0 offset:128
	s_waitcnt lgkmcnt(0)
	v_mfma_f32_32x32x16_bf16 v[80:95], v[10:13], v[108:111], v[80:95]
	v_mfma_f32_32x32x16_bf16 v[64:79], v[6:9], v[108:111], v[64:79]
	ds_read_b128 v[6:9], v0 offset:6816
	ds_read_b128 v[10:13], v0 offset:160
	s_waitcnt lgkmcnt(0)
	v_mfma_f32_32x32x16_bf16 v[80:95], v[10:13], v[104:107], v[80:95]
	v_mfma_f32_32x32x16_bf16 v[64:79], v[6:9], v[104:107], v[64:79]
	s_nop 10
	v_max_f32_e32 v0, v80, v81
	v_max3_f32 v0, v0, v82, v83
	v_max3_f32 v0, v0, v84, v85
	v_max3_f32 v0, v0, v86, v87
	v_max3_f32 v0, v0, v88, v89
	v_max3_f32 v0, v0, v90, v91
	v_max3_f32 v0, v0, v92, v93
	v_max3_f32 v0, v0, v94, v95
	v_max3_f32 v0, v0, v64, v65
	v_max3_f32 v0, v0, v66, v67
	v_max3_f32 v0, v0, v68, v69
	v_max3_f32 v0, v0, v70, v71
	v_max3_f32 v0, v0, v72, v73
	v_max3_f32 v0, v0, v74, v75
	v_max3_f32 v0, v0, v76, v77
	v_max3_f32 v0, v0, v78, v79
	ds_bpermute_b32 v6, v129, v0
	s_waitcnt lgkmcnt(0)
	v_max_f32_e32 v6, v6, v6
	v_max_f32_e32 v0, v0, v6
	v_cmp_lt_f32_e32 vcc, s2, v0
	s_cbranch_vccz .LBB0_243
; DI float ex2(float x) { return __builtin_amdgcn_exp2f(x); }
; template <int MODE>
; DI void attn_unit(LAS unsigned char* lds, const bf16_t* Qg, int ldq, const bf16_t* Kg, int ldk, const bf16_t* VTg, int ldvt, bf16_t* Og, int ldo,
;                   int q0, int NT, const float* gout, const float* relb, float lam, float osc, const float* qgain) {
;     ...
;                 if (t == 0 || __any(mx > 8.f)) {
;                     const float dl = (t == 0) ? mx : __builtin_fmaxf(mx, 0.f);
;                     mhat += dl;
; #pragma unroll
;                     for (int i = 0; i < 16; ++i) { p0[i] -= dl; p1[i] -= dl; }
; #pragma unroll
;                     for (int i = 0; i < 16; ++i) negm[i] = c15 - mhat;
;                     if (t > 0) { const float f = ex2(-dl); lrun *= f;
; #pragma unroll
;                         for (int d = 0; d < NDB; ++d)
; #pragma unroll
;                             for (int i = 0; i < 16; ++i) o[d][i] *= f; }
;                 }
;                 float rs = 0.f;
; #pragma unroll
;                 for (int i = 0; i < 16; ++i) { p0[i] = ex2(p0[i]); p1[i] = ex2(p1[i]); rs += p0[i] + p1[i]; }
;                 lrun += rs;
;             } else {
;                 f32x16 L0, L1;
;                 const bool diag = (NT - 1 - t) == TD;
;                 sb_prep(p0, L0, key0 + 4 * hi, qrow, diag); sb_prep(p1, L1, key0 + 32 + 4 * hi, qrow, diag);
;                 float own[8], par[8];
; #pragma unroll
;                 for (int g = 0; g < 4; ++g) { own[g] = (L0[4 * g] + L0[4 * g + 1]) + (L0[4 * g + 2] + L0[4 * g + 3]); own[4 + g] = (L1[4 * g] + L1[4 * g + 1]) + (L1[4 * g + 2] + L1[4 * g + 3]); }
; #pragma unroll
;                 for (int g = 0; g < 8; ++g) par[g] = shx(own[g], 32, lane);
;                 float so = 0.f, sp2 = 0.f;
; #pragma unroll
;                 for (int g = 7; g >= 0; --g) {
;                     const float SG = R + so + sp2 + (hi == 0 ? par[g] : 0.f);
;                     float w = 0.f;
; #pragma unroll
;                     for (int e = 3; e >= 0; --e) { const int idx = 4 * (g & 3) + e;
;                         if (g >= 4) { p1[idx] = ex2(p1[idx] + SG + w); w += L1[idx]; } else { p0[idx] = ex2(p0[idx] + SG + w); w += L0[idx]; } }
;                     so += own[g]; sp2 += par[g];
;                 }
;                 R += so + sp2;
;             }
; #pragma unroll
	v_max_f32_e32 v0, v0, v0
	v_max_f32_e32 v0, 0, v0
	v_pk_add_f32 v[64:65], v[64:65], v[0:1] op_sel_hi:[1,0] neg_lo:[0,1] neg_hi:[0,1]
	v_pk_add_f32 v[66:67], v[66:67], v[0:1] op_sel_hi:[1,0] neg_lo:[0,1] neg_hi:[0,1]
	v_pk_add_f32 v[68:69], v[68:69], v[0:1] op_sel_hi:[1,0] neg_lo:[0,1] neg_hi:[0,1]
	v_pk_add_f32 v[70:71], v[70:71], v[0:1] op_sel_hi:[1,0] neg_lo:[0,1] neg_hi:[0,1]
	v_pk_add_f32 v[72:73], v[72:73], v[0:1] op_sel_hi:[1,0] neg_lo:[0,1] neg_hi:[0,1]
	v_pk_add_f32 v[74:75], v[74:75], v[0:1] op_sel_hi:[1,0] neg_lo:[0,1] neg_hi:[0,1]
	v_pk_add_f32 v[76:77], v[76:77], v[0:1] op_sel_hi:[1,0] neg_lo:[0,1] neg_hi:[0,1]
	v_pk_add_f32 v[78:79], v[78:79], v[0:1] op_sel_hi:[1,0] neg_lo:[0,1] neg_hi:[0,1]
	v_pk_add_f32 v[80:81], v[80:81], v[0:1] op_sel_hi:[1,0] neg_lo:[0,1] neg_hi:[0,1]
	v_pk_add_f32 v[82:83], v[82:83], v[0:1] op_sel_hi:[1,0] neg_lo:[0,1] neg_hi:[0,1]
	v_pk_add_f32 v[84:85], v[84:85], v[0:1] op_sel_hi:[1,0] neg_lo:[0,1] neg_hi:[0,1]
	v_pk_add_f32 v[86:87], v[86:87], v[0:1] op_sel_hi:[1,0] neg_lo:[0,1] neg_hi:[0,1]
	v_pk_add_f32 v[88:89], v[88:89], v[0:1] op_sel_hi:[1,0] neg_lo:[0,1] neg_hi:[0,1]
	v_pk_add_f32 v[90:91], v[90:91], v[0:1] op_sel_hi:[1,0] neg_lo:[0,1] neg_hi:[0,1]
	v_pk_add_f32 v[92:93], v[92:93], v[0:1] op_sel_hi:[1,0] neg_lo:[0,1] neg_hi:[0,1]
	v_pk_add_f32 v[94:95], v[94:95], v[0:1] op_sel_hi:[1,0] neg_lo:[0,1] neg_hi:[0,1]
	v_add_f32_e32 v132, v132, v0
	v_exp_f32_e64 v0, -v0
	v_sub_f32_e32 v48, 0, v132
	v_mov_b32_e32 v49, v48
	v_mov_b32_e32 v50, v48
	v_mov_b32_e32 v51, v48
	v_mov_b32_e32 v52, v48
	v_mov_b32_e32 v53, v48
	v_mov_b32_e32 v54, v48
	v_mov_b32_e32 v55, v48
	v_mov_b32_e32 v56, v48
	v_mov_b32_e32 v57, v48
	v_mov_b32_e32 v58, v48
	v_mov_b32_e32 v59, v48
	v_mov_b32_e32 v60, v48
	v_mov_b32_e32 v61, v48
	v_mov_b32_e32 v62, v48
	v_mov_b32_e32 v63, v48
	v_pk_mul_f32 v[46:47], v[46:47], v[0:1] op_sel_hi:[1,0]
	v_pk_mul_f32 v[44:45], v[44:45], v[0:1] op_sel_hi:[1,0]
	v_pk_mul_f32 v[42:43], v[42:43], v[0:1] op_sel_hi:[1,0]
	v_pk_mul_f32 v[40:41], v[40:41], v[0:1] op_sel_hi:[1,0]
	v_pk_mul_f32 v[38:39], v[38:39], v[0:1] op_sel_hi:[1,0]
	v_pk_mul_f32 v[36:37], v[36:37], v[0:1] op_sel_hi:[1,0]
	v_pk_mul_f32 v[34:35], v[34:35], v[0:1] op_sel_hi:[1,0]
	v_pk_mul_f32 v[32:33], v[32:33], v[0:1] op_sel_hi:[1,0]
	v_pk_mul_f32 v[30:31], v[30:31], v[0:1] op_sel_hi:[1,0]
	v_pk_mul_f32 v[28:29], v[28:29], v[0:1] op_sel_hi:[1,0]
	v_pk_mul_f32 v[26:27], v[26:27], v[0:1] op_sel_hi:[1,0]
	v_pk_mul_f32 v[24:25], v[24:25], v[0:1] op_sel_hi:[1,0]
	v_pk_mul_f32 v[22:23], v[22:23], v[0:1] op_sel_hi:[1,0]
	v_pk_mul_f32 v[20:21], v[20:21], v[0:1] op_sel_hi:[1,0]
	v_pk_mul_f32 v[18:19], v[18:19], v[0:1] op_sel_hi:[1,0]
	v_pk_mul_f32 v[16:17], v[16:17], v[0:1] op_sel_hi:[1,0]
	v_mul_f32_e32 v133, v133, v0
.LBB0_243:
	v_exp_f32_e32 v159, v80
	v_exp_f32_e32 v173, v64
	v_exp_f32_e32 v158, v81
	v_exp_f32_e32 v0, v65
	v_exp_f32_e32 v155, v82
	v_exp_f32_e32 v157, v66
	v_exp_f32_e32 v154, v83
	v_exp_f32_e32 v156, v67
	v_exp_f32_e32 v151, v84
	v_exp_f32_e32 v153, v68
	v_exp_f32_e32 v150, v85
	v_exp_f32_e32 v152, v69
	v_exp_f32_e32 v145, v86
	v_exp_f32_e32 v147, v70
	v_exp_f32_e32 v144, v87
	v_exp_f32_e32 v146, v71
	v_exp_f32_e32 v87, v88
	v_exp_f32_e32 v172, v72
	v_exp_f32_e32 v86, v89
	v_exp_f32_e32 v88, v73
	v_exp_f32_e32 v83, v90
	v_exp_f32_e32 v85, v74
	v_exp_f32_e32 v82, v91
	v_exp_f32_e32 v84, v75
	v_exp_f32_e32 v81, v92
	v_exp_f32_e32 v90, v76
	v_exp_f32_e32 v76, v93
	v_exp_f32_e32 v80, v77
	v_exp_f32_e32 v73, v94
	v_exp_f32_e32 v75, v78
	v_exp_f32_e32 v72, v95
	v_exp_f32_e32 v74, v79
	v_cvt_pk_bf16_f32 v68, v159, v158
	v_cvt_pk_bf16_f32 v64, v87, v86
	v_cvt_pk_bf16_f32 v10, v173, v0
	v_cvt_pk_bf16_f32 v6, v172, v88
	v_cvt_pk_bf16_f32 v69, v155, v154
	v_cvt_pk_bf16_f32 v65, v83, v82
	v_cvt_pk_bf16_f32 v11, v157, v156
	v_cvt_pk_bf16_f32 v7, v85, v84
	v_cvt_pk_bf16_f32 v70, v151, v150
	v_cvt_pk_bf16_f32 v66, v81, v76
	v_cvt_pk_bf16_f32 v12, v153, v152
	v_cvt_pk_bf16_f32 v8, v90, v80
	v_cvt_pk_bf16_f32 v71, v145, v144
	v_cvt_pk_bf16_f32 v67, v73, v72
	v_cvt_pk_bf16_f32 v13, v147, v146
	s_and_b64 vcc, exec, s[42:43]
	v_cvt_pk_bf16_f32 v9, v75, v74
	s_cbranch_vccnz .LBB0_245
	s_mul_i32 s2, s11, 0x4400
	v_add_u32_e32 v240, s2, v163
	v_add_u32_e32 v236, 0x8800, v240
	v_add_u32_e32 v237, 0x9800, v240
	ds_read2_b64 v[212:215], v236 offset1:2
	ds_read2_b64 v[216:219], v236 offset0:4 offset1:6
	ds_read2_b64 v[220:223], v236 offset0:8 offset1:10
	ds_read2_b64 v[224:227], v236 offset0:12 offset1:14
	s_waitcnt lgkmcnt(2)
	v_mfma_f32_32x32x16_bf16 v[32:47], v[212:215], v[68:71], v[32:47]
	v_mfma_f32_32x32x16_bf16 v[32:47], v[216:219], v[64:67], v[32:47]
	ds_read2_b64 v[212:215], v237 offset0:32 offset1:34
	ds_read2_b64 v[216:219], v237 offset0:36 offset1:38
	s_waitcnt lgkmcnt(2)
	v_mfma_f32_32x32x16_bf16 v[32:47], v[220:223], v[10:13], v[32:47]
	v_mfma_f32_32x32x16_bf16 v[32:47], v[224:227], v[6:9], v[32:47]
	ds_read2_b64 v[220:223], v237 offset0:40 offset1:42
	ds_read2_b64 v[224:227], v237 offset0:44 offset1:46
	s_waitcnt lgkmcnt(2)
	v_mfma_f32_32x32x16_bf16 v[16:31], v[212:215], v[68:71], v[16:31]
	v_mfma_f32_32x32x16_bf16 v[16:31], v[216:219], v[64:67], v[16:31]
	s_waitcnt lgkmcnt(0)
	v_mfma_f32_32x32x16_bf16 v[16:31], v[220:223], v[10:13], v[16:31]
	v_mfma_f32_32x32x16_bf16 v[16:31], v[224:227], v[6:9], v[16:31]

.LBB0_246:
	s_cmp_eq_u32 s6, 0
	s_cselect_b32 s2, 0x4400, 0
	v_add3_u32 v0, s2, v168, v169
	s_waitcnt vmcnt(0) lgkmcnt(0)
	ds_write_b128 v0, v[96:99]
.LBB0_248:
	s_and_saveexec_b64 s[6:7], s[40:41]
	s_cbranch_execz .LBB0_233
	v_add3_u32 v0, s2, v165, v166
	ds_write_b128 v0, v[100:103]
	s_branch .LBB0_233

; #define PG8_STAGE(bufoff, gbase, voff) do { _Pragma("unroll") for (int _i = 0; _i < 2; ++_i) \
;         __builtin_amdgcn_global_load_lds((const unsigned*)((const char*)(gbase) + (voff)[_i]), (LAS unsigned*)(lds + (bufoff) + ldsw + _i * 8192), 16, 0, 0); } while (0)
; #define PG8_LDA(dst, b, h) do { _Pragma("unroll") for (int m = 0; m < 4; ++m) _Pragma("unroll") for (int k = 0; k < 2; ++k) dst[m][k] = *(const LAS bf16x8*)(lds + PG8_SA(b, h) + aoff + m * 2048 + k * 1024); } while (0)
; #define PG8_LDB(dst, b, h) do { _Pragma("unroll") for (int n = 0; n < 2; ++n) _Pragma("unroll") for (int k = 0; k < 2; ++k) dst[n][k] = *(const LAS bf16x8*)(lds + PG8_SB(b, h) + boff + n * 2048 + k * 1024); } while (0)
; #define PG8_MMA(ai, bj, At, Bt) do { __builtin_amdgcn_s_setprio(1); _Pragma("unroll") for (int m = 0; m < 4; ++m) _Pragma("unroll") for (int n = 0; n < 2; ++n) _Pragma("unroll") for (int k = 0; k < 2; ++k) \
;         acc[ai][bj][m][n] = __builtin_amdgcn_mfma_f32_16x16x32_bf16(Bt[n][k], At[m][k], acc[ai][bj][m][n], 0, 0, 0); __builtin_amdgcn_s_setprio(0); } while (0)
; #define PG8_WAIT_V(n) asm volatile("s_waitcnt vmcnt(" #n ")" ::: "memory")
; #define PG8_WAIT_L(n) asm volatile("s_waitcnt lgkmcnt(" #n ")" ::: "memory")
; #define PG8_BAR __builtin_amdgcn_s_barrier()
; #define PG8_SCHED __builtin_amdgcn_sched_barrier(0)
; template <class Epi>
; DI void gemm_phase(LAS unsigned char* lds, const Gemm g, const StaticOrder& S, const Epi& E) {
;     ...
;             PG8_LDB(B0, 0, 0); PG8_LDB(B1, 0, 1); PG8_SCHED; PG8_LDA(At, 0, 0); PG8_STAGE(PG8_SA(1, 1), a1 + hstepA, voffA);
;             PG8_WAIT_V(8); PG8_WAIT_L(0); PG8_BAR; PG8_MMA(0, 0, At, B0); PG8_MMA(0, 1, At, B1); PG8_BAR; PG8_SCHED;
;             PG8_LDA(At, 0, 1); PG8_STAGE(PG8_SB(0, 0), b2, voffB); PG8_STAGE(PG8_SB(0, 1), b2 + hstepB, voffB); PG8_STAGE(PG8_SA(0, 0), a2, voffA);
;             PG8_WAIT_V(8); PG8_WAIT_L(0); PG8_BAR; PG8_MMA(1, 0, At, B0); PG8_MMA(1, 1, At, B1); PG8_BAR; PG8_SCHED;
.LBB0_446:
	s_add_i32 s2, s33, 2
	s_add_u32 s3, s0, 0x80
	s_addc_u32 s36, s1, 0
	s_add_i32 s50, 0, 0x10000
	s_cmp_eq_u32 s18, s33
	s_cselect_b32 s37, s31, s36
	s_cselect_b32 s36, s30, s3
	v_add_u32_e32 v0, s50, v238
	s_cselect_b32 s49, s27, s29
	s_cselect_b32 s48, s26, s16
	s_add_i32 s3, 0, 0x14000
	s_waitcnt lgkmcnt(0)
	ds_read_b128 v[130:133], v0
	ds_read_b128 v[134:137], v0 offset:1024
	ds_read_b128 v[138:141], v0 offset:2048
	ds_read_b128 v[142:145], v0 offset:3072
	v_add_u32_e32 v0, s3, v238
	ds_read_b128 v[146:149], v0
	ds_read_b128 v[150:153], v0 offset:1024
	ds_read_b128 v[154:157], v0 offset:2048
	ds_read_b128 v[158:161], v0 offset:3072
	v_lshl_add_u64 v[194:195], s[0:1], 0, v[214:215]
	s_add_i32 m0, s13, 0xc000
	ds_read_b128 v[162:165], v245
	ds_read_b128 v[166:169], v245 offset:1024
	ds_read_b128 v[170:173], v245 offset:2048
	ds_read_b128 v[174:177], v245 offset:3072
	ds_read_b128 v[178:181], v245 offset:4096
	ds_read_b128 v[182:185], v245 offset:5120
	ds_read_b128 v[186:189], v245 offset:6144
	ds_read_b128 v[190:193], v245 offset:7168
	global_load_lds_dwordx4 v[194:195], off
	s_add_i32 m0, s13, 0xe000
	v_lshl_add_u64 v[194:195], s[0:1], 0, v[212:213]
	global_load_lds_dwordx4 v[194:195], off
	s_waitcnt vmcnt(8)
	s_waitcnt lgkmcnt(0)
	s_barrier
	s_setprio 1
	s_waitcnt lgkmcnt(0)
	v_mfma_f32_16x16x32_bf16 v[126:129], v[130:133], v[162:165], v[126:129]
	v_mfma_f32_16x16x32_bf16 v[122:125], v[138:141], v[162:165], v[122:125]
	v_mfma_f32_16x16x32_bf16 v[110:113], v[130:133], v[170:173], v[110:113]
	v_mfma_f32_16x16x32_bf16 v[106:109], v[138:141], v[170:173], v[106:109]
	v_mfma_f32_16x16x32_bf16 v[94:97], v[130:133], v[178:181], v[94:97]
	v_mfma_f32_16x16x32_bf16 v[90:93], v[138:141], v[178:181], v[90:93]
	v_mfma_f32_16x16x32_bf16 v[78:81], v[130:133], v[186:189], v[78:81]
	v_mfma_f32_16x16x32_bf16 v[74:77], v[138:141], v[186:189], v[74:77]
	v_mfma_f32_16x16x32_bf16 v[126:129], v[134:137], v[166:169], v[126:129]
	v_mfma_f32_16x16x32_bf16 v[122:125], v[142:145], v[166:169], v[122:125]
	v_mfma_f32_16x16x32_bf16 v[110:113], v[134:137], v[174:177], v[110:113]
	v_mfma_f32_16x16x32_bf16 v[106:109], v[142:145], v[174:177], v[106:109]
	v_mfma_f32_16x16x32_bf16 v[94:97], v[134:137], v[182:185], v[94:97]
	v_mfma_f32_16x16x32_bf16 v[90:93], v[142:145], v[182:185], v[90:93]
	v_mfma_f32_16x16x32_bf16 v[78:81], v[134:137], v[190:193], v[78:81]
	v_mfma_f32_16x16x32_bf16 v[74:77], v[142:145], v[190:193], v[74:77]
	s_setprio 0
	s_setprio 1
	v_mfma_f32_16x16x32_bf16 v[118:121], v[146:149], v[162:165], v[118:121]
	v_mfma_f32_16x16x32_bf16 v[114:117], v[154:157], v[162:165], v[114:117]
	v_mfma_f32_16x16x32_bf16 v[102:105], v[146:149], v[170:173], v[102:105]
	v_mfma_f32_16x16x32_bf16 v[98:101], v[154:157], v[170:173], v[98:101]
	v_mfma_f32_16x16x32_bf16 v[86:89], v[146:149], v[178:181], v[86:89]
	v_mfma_f32_16x16x32_bf16 v[82:85], v[154:157], v[178:181], v[82:85]
	v_mfma_f32_16x16x32_bf16 v[70:73], v[146:149], v[186:189], v[70:73]
	v_mfma_f32_16x16x32_bf16 v[66:69], v[154:157], v[186:189], v[66:69]
	v_mfma_f32_16x16x32_bf16 v[118:121], v[150:153], v[166:169], v[118:121]
	v_mfma_f32_16x16x32_bf16 v[114:117], v[158:161], v[166:169], v[114:117]
	v_mfma_f32_16x16x32_bf16 v[102:105], v[150:153], v[174:177], v[102:105]
	v_mfma_f32_16x16x32_bf16 v[98:101], v[158:161], v[174:177], v[98:101]
	v_mfma_f32_16x16x32_bf16 v[86:89], v[150:153], v[182:185], v[86:89]
	v_mfma_f32_16x16x32_bf16 v[82:85], v[158:161], v[182:185], v[82:85]
	v_mfma_f32_16x16x32_bf16 v[70:73], v[150:153], v[190:193], v[70:73]
	v_mfma_f32_16x16x32_bf16 v[66:69], v[158:161], v[190:193], v[66:69]
	s_setprio 0
	s_barrier
	s_add_i32 s33, s50, s12
	v_lshl_add_u64 v[194:195], s[48:49], 0, v[200:201]
	s_mov_b32 m0, s33
	ds_read_b128 v[162:165], v245 offset:16384
	ds_read_b128 v[166:169], v245 offset:17408
	ds_read_b128 v[170:173], v245 offset:18432
	ds_read_b128 v[174:177], v245 offset:19456
	ds_read_b128 v[178:181], v245 offset:20480
	ds_read_b128 v[182:185], v245 offset:21504
	ds_read_b128 v[186:189], v245 offset:22528
	ds_read_b128 v[190:193], v245 offset:23552
	global_load_lds_dwordx4 v[194:195], off
	s_add_i32 m0, s33, 0x2000
	v_lshl_add_u64 v[196:197], s[48:49], 0, v[204:205]
	s_add_u32 s48, s48, s9
	s_addc_u32 s49, s49, 0
	s_add_i32 s3, s3, s12
	global_load_lds_dwordx4 v[196:197], off
	v_lshl_add_u64 v[216:217], s[48:49], 0, v[200:201]
	s_mov_b32 m0, s3
	v_lshl_add_u64 v[218:219], s[48:49], 0, v[204:205]
	global_load_lds_dwordx4 v[216:217], off
	s_add_i32 m0, s3, 0x2000
	v_lshl_add_u64 v[220:221], s[36:37], 0, v[198:199]
	global_load_lds_dwordx4 v[218:219], off
	s_mov_b32 m0, s13
	v_lshl_add_u64 v[222:223], s[36:37], 0, v[202:203]
	global_load_lds_dwordx4 v[220:221], off
	s_mov_b32 m0, s72
	s_nop 0
	global_load_lds_dwordx4 v[222:223], off
	s_waitcnt vmcnt(8)
	s_waitcnt lgkmcnt(0)
	s_barrier
; #define PG8_STAGE(bufoff, gbase, voff) do { _Pragma("unroll") for (int _i = 0; _i < 2; ++_i) \
;         __builtin_amdgcn_global_load_lds((const unsigned*)((const char*)(gbase) + (voff)[_i]), (LAS unsigned*)(lds + (bufoff) + ldsw + _i * 8192), 16, 0, 0); } while (0)
; #define PG8_LDA(dst, b, h) do { _Pragma("unroll") for (int m = 0; m < 4; ++m) _Pragma("unroll") for (int k = 0; k < 2; ++k) dst[m][k] = *(const LAS bf16x8*)(lds + PG8_SA(b, h) + aoff + m * 2048 + k * 1024); } while (0)
; #define PG8_LDB(dst, b, h) do { _Pragma("unroll") for (int n = 0; n < 2; ++n) _Pragma("unroll") for (int k = 0; k < 2; ++k) dst[n][k] = *(const LAS bf16x8*)(lds + PG8_SB(b, h) + boff + n * 2048 + k * 1024); } while (0)
; #define PG8_MMA(ai, bj, At, Bt) do { __builtin_amdgcn_s_setprio(1); _Pragma("unroll") for (int m = 0; m < 4; ++m) _Pragma("unroll") for (int n = 0; n < 2; ++n) _Pragma("unroll") for (int k = 0; k < 2; ++k) \
;         acc[ai][bj][m][n] = __builtin_amdgcn_mfma_f32_16x16x32_bf16(Bt[n][k], At[m][k], acc[ai][bj][m][n], 0, 0, 0); __builtin_amdgcn_s_setprio(0); } while (0)
; #define PG8_WAIT_V(n) asm volatile("s_waitcnt vmcnt(" #n ")" ::: "memory")
; #define PG8_WAIT_L(n) asm volatile("s_waitcnt lgkmcnt(" #n ")" ::: "memory")
; #define PG8_BAR __builtin_amdgcn_s_barrier()
; #define PG8_SCHED __builtin_amdgcn_sched_barrier(0)
; template <class Epi>
; DI void gemm_phase(LAS unsigned char* lds, const Gemm g, const StaticOrder& S, const Epi& E) {
;     ...
;             PG8_WAIT_V(8); PG8_WAIT_L(0); PG8_BAR; PG8_MMA(1, 0, At, B0); PG8_MMA(1, 1, At, B1); PG8_BAR; PG8_SCHED;
;             PG8_LDB(B0, 1, 0); PG8_LDB(B1, 1, 1); PG8_SCHED; PG8_LDA(At, 1, 0); PG8_STAGE(PG8_SA(0, 1), a2 + hstepA, voffA);
;             PG8_WAIT_V(8); PG8_WAIT_L(0); PG8_BAR; PG8_MMA(0, 0, At, B0); PG8_MMA(0, 1, At, B1); PG8_BAR; PG8_SCHED;
	s_setprio 1
	s_waitcnt lgkmcnt(0)
	v_mfma_f32_16x16x32_bf16 v[62:65], v[130:133], v[162:165], v[62:65]
	v_mfma_f32_16x16x32_bf16 v[58:61], v[138:141], v[162:165], v[58:61]
	v_mfma_f32_16x16x32_bf16 v[46:49], v[130:133], v[170:173], v[46:49]
	v_mfma_f32_16x16x32_bf16 v[42:45], v[138:141], v[170:173], v[42:45]
	v_mfma_f32_16x16x32_bf16 v[30:33], v[130:133], v[178:181], v[30:33]
	v_mfma_f32_16x16x32_bf16 v[26:29], v[138:141], v[178:181], v[26:29]
	v_mfma_f32_16x16x32_bf16 v[14:17], v[130:133], v[186:189], v[14:17]
	v_mfma_f32_16x16x32_bf16 v[10:13], v[138:141], v[186:189], v[10:13]
	v_mfma_f32_16x16x32_bf16 v[62:65], v[134:137], v[166:169], v[62:65]
	v_mfma_f32_16x16x32_bf16 v[58:61], v[142:145], v[166:169], v[58:61]
	v_mfma_f32_16x16x32_bf16 v[46:49], v[134:137], v[174:177], v[46:49]
	v_mfma_f32_16x16x32_bf16 v[42:45], v[142:145], v[174:177], v[42:45]
	v_mfma_f32_16x16x32_bf16 v[30:33], v[134:137], v[182:185], v[30:33]
	v_mfma_f32_16x16x32_bf16 v[26:29], v[142:145], v[182:185], v[26:29]
	v_mfma_f32_16x16x32_bf16 v[14:17], v[134:137], v[190:193], v[14:17]
	v_mfma_f32_16x16x32_bf16 v[10:13], v[142:145], v[190:193], v[10:13]
	s_setprio 0
	s_setprio 1
	v_mfma_f32_16x16x32_bf16 v[54:57], v[146:149], v[162:165], v[54:57]
	v_mfma_f32_16x16x32_bf16 v[50:53], v[154:157], v[162:165], v[50:53]
	v_mfma_f32_16x16x32_bf16 v[38:41], v[146:149], v[170:173], v[38:41]
	v_mfma_f32_16x16x32_bf16 v[34:37], v[154:157], v[170:173], v[34:37]
	v_mfma_f32_16x16x32_bf16 v[22:25], v[146:149], v[178:181], v[22:25]
	v_mfma_f32_16x16x32_bf16 v[18:21], v[154:157], v[178:181], v[18:21]
	v_mfma_f32_16x16x32_bf16 v[6:9], v[146:149], v[186:189], v[6:9]
	v_mfma_f32_16x16x32_bf16 v[2:5], v[154:157], v[186:189], v[2:5]
	v_mfma_f32_16x16x32_bf16 v[54:57], v[150:153], v[166:169], v[54:57]
	v_mfma_f32_16x16x32_bf16 v[50:53], v[158:161], v[166:169], v[50:53]
	v_mfma_f32_16x16x32_bf16 v[38:41], v[150:153], v[174:177], v[38:41]
	v_mfma_f32_16x16x32_bf16 v[34:37], v[158:161], v[174:177], v[34:37]
	v_mfma_f32_16x16x32_bf16 v[22:25], v[150:153], v[182:185], v[22:25]
	v_mfma_f32_16x16x32_bf16 v[18:21], v[158:161], v[182:185], v[18:21]
	v_mfma_f32_16x16x32_bf16 v[6:9], v[150:153], v[190:193], v[6:9]
	v_mfma_f32_16x16x32_bf16 v[2:5], v[158:161], v[190:193], v[2:5]
	s_setprio 0
	s_barrier
	s_add_i32 s3, 0, 0x18000
	v_add_u32_e32 v0, s3, v238
	s_add_i32 s33, 0, 0x1c000
	ds_read_b128 v[130:133], v0
	ds_read_b128 v[134:137], v0 offset:1024
	ds_read_b128 v[138:141], v0 offset:2048
	ds_read_b128 v[142:145], v0 offset:3072
	v_add_u32_e32 v0, s33, v238
	ds_read_b128 v[146:149], v0
	ds_read_b128 v[150:153], v0 offset:1024
	ds_read_b128 v[154:157], v0 offset:2048
	ds_read_b128 v[158:161], v0 offset:3072
	s_add_u32 s36, s36, s56
	s_addc_u32 s37, s37, 0
	s_mov_b32 m0, s73
	v_lshl_add_u64 v[224:225], s[36:37], 0, v[198:199]
	ds_read_b128 v[162:165], v245 offset:32768
	ds_read_b128 v[166:169], v245 offset:33792
	ds_read_b128 v[170:173], v245 offset:34816
	ds_read_b128 v[174:177], v245 offset:35840
	ds_read_b128 v[178:181], v245 offset:36864
	ds_read_b128 v[182:185], v245 offset:37888
	ds_read_b128 v[186:189], v245 offset:38912
	ds_read_b128 v[190:193], v245 offset:39936
	global_load_lds_dwordx4 v[224:225], off
	s_mov_b32 m0, s74
	v_lshl_add_u64 v[224:225], s[36:37], 0, v[202:203]
	global_load_lds_dwordx4 v[224:225], off
	s_waitcnt vmcnt(8)
	s_waitcnt lgkmcnt(0)
	s_barrier
	s_setprio 1
	s_waitcnt lgkmcnt(0)
	v_mfma_f32_16x16x32_bf16 v[126:129], v[130:133], v[162:165], v[126:129]
	v_mfma_f32_16x16x32_bf16 v[122:125], v[138:141], v[162:165], v[122:125]
	v_mfma_f32_16x16x32_bf16 v[110:113], v[130:133], v[170:173], v[110:113]
	v_mfma_f32_16x16x32_bf16 v[106:109], v[138:141], v[170:173], v[106:109]
	v_mfma_f32_16x16x32_bf16 v[94:97], v[130:133], v[178:181], v[94:97]
	v_mfma_f32_16x16x32_bf16 v[90:93], v[138:141], v[178:181], v[90:93]
	v_mfma_f32_16x16x32_bf16 v[78:81], v[130:133], v[186:189], v[78:81]
	v_mfma_f32_16x16x32_bf16 v[74:77], v[138:141], v[186:189], v[74:77]
	v_mfma_f32_16x16x32_bf16 v[126:129], v[134:137], v[166:169], v[126:129]
	v_mfma_f32_16x16x32_bf16 v[122:125], v[142:145], v[166:169], v[122:125]
	v_mfma_f32_16x16x32_bf16 v[110:113], v[134:137], v[174:177], v[110:113]
	v_mfma_f32_16x16x32_bf16 v[106:109], v[142:145], v[174:177], v[106:109]
	v_mfma_f32_16x16x32_bf16 v[94:97], v[134:137], v[182:185], v[94:97]
	v_mfma_f32_16x16x32_bf16 v[90:93], v[142:145], v[182:185], v[90:93]
	v_mfma_f32_16x16x32_bf16 v[78:81], v[134:137], v[190:193], v[78:81]
	v_mfma_f32_16x16x32_bf16 v[74:77], v[142:145], v[190:193], v[74:77]
	s_setprio 0
	s_setprio 1
	v_mfma_f32_16x16x32_bf16 v[118:121], v[146:149], v[162:165], v[118:121]
	v_mfma_f32_16x16x32_bf16 v[114:117], v[154:157], v[162:165], v[114:117]
	v_mfma_f32_16x16x32_bf16 v[102:105], v[146:149], v[170:173], v[102:105]
	v_mfma_f32_16x16x32_bf16 v[98:101], v[154:157], v[170:173], v[98:101]
	v_mfma_f32_16x16x32_bf16 v[86:89], v[146:149], v[178:181], v[86:89]
	v_mfma_f32_16x16x32_bf16 v[82:85], v[154:157], v[178:181], v[82:85]
	v_mfma_f32_16x16x32_bf16 v[70:73], v[146:149], v[186:189], v[70:73]
	v_mfma_f32_16x16x32_bf16 v[66:69], v[154:157], v[186:189], v[66:69]
	v_mfma_f32_16x16x32_bf16 v[118:121], v[150:153], v[166:169], v[118:121]
	v_mfma_f32_16x16x32_bf16 v[114:117], v[158:161], v[166:169], v[114:117]
	v_mfma_f32_16x16x32_bf16 v[102:105], v[150:153], v[174:177], v[102:105]
	v_mfma_f32_16x16x32_bf16 v[98:101], v[158:161], v[174:177], v[98:101]
	v_mfma_f32_16x16x32_bf16 v[86:89], v[150:153], v[182:185], v[86:89]
	v_mfma_f32_16x16x32_bf16 v[82:85], v[158:161], v[182:185], v[82:85]
	v_mfma_f32_16x16x32_bf16 v[70:73], v[150:153], v[190:193], v[70:73]
	v_mfma_f32_16x16x32_bf16 v[66:69], v[158:161], v[190:193], v[66:69]
	s_setprio 0
	s_barrier
; #define PG8_STAGE(bufoff, gbase, voff) do { _Pragma("unroll") for (int _i = 0; _i < 2; ++_i) \
;         __builtin_amdgcn_global_load_lds((const unsigned*)((const char*)(gbase) + (voff)[_i]), (LAS unsigned*)(lds + (bufoff) + ldsw + _i * 8192), 16, 0, 0); } while (0)
; #define PG8_LDA(dst, b, h) do { _Pragma("unroll") for (int m = 0; m < 4; ++m) _Pragma("unroll") for (int k = 0; k < 2; ++k) dst[m][k] = *(const LAS bf16x8*)(lds + PG8_SA(b, h) + aoff + m * 2048 + k * 1024); } while (0)
; #define PG8_MMA(ai, bj, At, Bt) do { __builtin_amdgcn_s_setprio(1); _Pragma("unroll") for (int m = 0; m < 4; ++m) _Pragma("unroll") for (int n = 0; n < 2; ++n) _Pragma("unroll") for (int k = 0; k < 2; ++k) \
;         acc[ai][bj][m][n] = __builtin_amdgcn_mfma_f32_16x16x32_bf16(Bt[n][k], At[m][k], acc[ai][bj][m][n], 0, 0, 0); __builtin_amdgcn_s_setprio(0); } while (0)
; #define PG8_WAIT_V(n) asm volatile("s_waitcnt vmcnt(" #n ")" ::: "memory")
; #define PG8_WAIT_L(n) asm volatile("s_waitcnt lgkmcnt(" #n ")" ::: "memory")
; #define PG8_BAR __builtin_amdgcn_s_barrier()
; #define PG8_SCHED __builtin_amdgcn_sched_barrier(0)
; template <class Epi>
; DI void gemm_phase(LAS unsigned char* lds, const Gemm g, const StaticOrder& S, const Epi& E) {
;     ...
;             PG8_LDA(At, 1, 1); PG8_STAGE(PG8_SB(1, 0), b3, voffB); PG8_STAGE(PG8_SB(1, 1), b3 + hstepB, voffB); PG8_STAGE(PG8_SA(1, 0), a3, voffA);
;             PG8_WAIT_V(8); PG8_WAIT_L(0); PG8_BAR; PG8_MMA(1, 0, At, B0); PG8_MMA(1, 1, At, B1); PG8_BAR; PG8_SCHED;
;         }
;         if (wr == 0) PG8_BAR;
;         E(acc, cur, wr, wc, fr, fq);
	s_add_i32 s3, s3, s12
	v_lshl_add_u64 v[194:195], v[194:195], 0, s[34:35]
	s_mov_b32 m0, s3
	ds_read_b128 v[162:165], v245 offset:49152
	ds_read_b128 v[166:169], v245 offset:50176
	ds_read_b128 v[170:173], v245 offset:51200
	ds_read_b128 v[174:177], v245 offset:52224
	ds_read_b128 v[178:181], v245 offset:53248
	ds_read_b128 v[182:185], v245 offset:54272
	ds_read_b128 v[186:189], v245 offset:55296
	ds_read_b128 v[190:193], v245 offset:56320
	global_load_lds_dwordx4 v[194:195], off
	v_lshl_add_u64 v[194:195], v[196:197], 0, s[34:35]
	s_add_i32 m0, s3, 0x2000
	s_add_i32 s3, s33, s12
	global_load_lds_dwordx4 v[194:195], off
	s_mov_b32 m0, s3
	v_lshl_add_u64 v[194:195], v[216:217], 0, s[34:35]
	global_load_lds_dwordx4 v[194:195], off
	s_add_i32 m0, s3, 0x2000
	v_lshl_add_u64 v[194:195], v[218:219], 0, s[34:35]
	global_load_lds_dwordx4 v[194:195], off
	s_mov_b32 m0, s75
	v_lshl_add_u64 v[194:195], v[220:221], 0, s[34:35]
	global_load_lds_dwordx4 v[194:195], off
	s_mov_b32 m0, s54
	v_lshl_add_u64 v[194:195], v[222:223], 0, s[34:35]
	global_load_lds_dwordx4 v[194:195], off
	s_waitcnt vmcnt(8)
	s_waitcnt lgkmcnt(0)
	s_barrier
	s_setprio 1
	s_waitcnt lgkmcnt(0)
	v_mfma_f32_16x16x32_bf16 v[62:65], v[130:133], v[162:165], v[62:65]
	v_mfma_f32_16x16x32_bf16 v[58:61], v[138:141], v[162:165], v[58:61]
	v_mfma_f32_16x16x32_bf16 v[46:49], v[130:133], v[170:173], v[46:49]
	v_mfma_f32_16x16x32_bf16 v[42:45], v[138:141], v[170:173], v[42:45]
	v_mfma_f32_16x16x32_bf16 v[30:33], v[130:133], v[178:181], v[30:33]
	v_mfma_f32_16x16x32_bf16 v[26:29], v[138:141], v[178:181], v[26:29]
	v_mfma_f32_16x16x32_bf16 v[14:17], v[130:133], v[186:189], v[14:17]
	v_mfma_f32_16x16x32_bf16 v[10:13], v[138:141], v[186:189], v[10:13]
	v_mfma_f32_16x16x32_bf16 v[62:65], v[134:137], v[166:169], v[62:65]
	v_mfma_f32_16x16x32_bf16 v[58:61], v[142:145], v[166:169], v[58:61]
	v_mfma_f32_16x16x32_bf16 v[46:49], v[134:137], v[174:177], v[46:49]
	v_mfma_f32_16x16x32_bf16 v[42:45], v[142:145], v[174:177], v[42:45]
	v_mfma_f32_16x16x32_bf16 v[30:33], v[134:137], v[182:185], v[30:33]
	v_mfma_f32_16x16x32_bf16 v[26:29], v[142:145], v[182:185], v[26:29]
	v_mfma_f32_16x16x32_bf16 v[14:17], v[134:137], v[190:193], v[14:17]
	v_mfma_f32_16x16x32_bf16 v[10:13], v[142:145], v[190:193], v[10:13]
	s_setprio 0
	s_setprio 1
	v_mfma_f32_16x16x32_bf16 v[54:57], v[146:149], v[162:165], v[54:57]
	v_mfma_f32_16x16x32_bf16 v[50:53], v[154:157], v[162:165], v[50:53]
	v_mfma_f32_16x16x32_bf16 v[38:41], v[146:149], v[170:173], v[38:41]
	v_mfma_f32_16x16x32_bf16 v[34:37], v[154:157], v[170:173], v[34:37]
	v_mfma_f32_16x16x32_bf16 v[22:25], v[146:149], v[178:181], v[22:25]
	v_mfma_f32_16x16x32_bf16 v[18:21], v[154:157], v[178:181], v[18:21]
	v_mfma_f32_16x16x32_bf16 v[6:9], v[146:149], v[186:189], v[6:9]
	v_mfma_f32_16x16x32_bf16 v[2:5], v[154:157], v[186:189], v[2:5]
	v_mfma_f32_16x16x32_bf16 v[54:57], v[150:153], v[166:169], v[54:57]
	v_mfma_f32_16x16x32_bf16 v[50:53], v[158:161], v[166:169], v[50:53]
	v_mfma_f32_16x16x32_bf16 v[38:41], v[150:153], v[174:177], v[38:41]
	v_mfma_f32_16x16x32_bf16 v[34:37], v[158:161], v[174:177], v[34:37]
	v_mfma_f32_16x16x32_bf16 v[22:25], v[150:153], v[182:185], v[22:25]
	v_mfma_f32_16x16x32_bf16 v[18:21], v[158:161], v[182:185], v[18:21]
	v_mfma_f32_16x16x32_bf16 v[6:9], v[150:153], v[190:193], v[6:9]
	v_mfma_f32_16x16x32_bf16 v[2:5], v[158:161], v[190:193], v[2:5]
	s_setprio 0
	s_barrier
	s_add_u32 s16, s16, 0x100
	s_addc_u32 s29, s29, 0
	s_add_u32 s0, s0, 0x100
	s_addc_u32 s1, s1, 0
	s_cmp_ge_u32 s2, s5
	s_mov_b32 s33, s2
	s_cbranch_scc0 .LBB0_446
	s_and_b64 vcc, exec, s[70:71]
	s_cbranch_vccz .LBB0_450
	s_barrier
	s_cmp_lt_i32 s24, 2
	s_mov_b64 s[0:1], -1
	s_cbranch_scc0 .LBB0_451
